# GEMM unit boundary: removed full VMEM drain before the K-loop; first two super-phases after an epilogue use waits relaxed by the 16 stores so the store drain overlaps MFMA
# baseline (speedup 1.0000x reference)
.LBB0_36:
	s_andn2_b64 vcc, exec, s[0:1]
	s_cbranch_vccnz .LBB0_57
	v_readlane_b32 s0, v253, 33
	v_mov_b32_e32 v8, v186
	v_readlane_b32 s1, v253, 34
	s_andn2_b64 vcc, exec, s[0:1]
	v_readfirstlane_b32 s6, v8
	s_cbranch_vccnz .LBB0_57
	s_mov_b32 s100, 0
	v_lshlrev_b32_e32 v0, 4, v8
	v_add_u32_e32 v3, 0x2000, v0
	v_ashrrev_i32_e32 v2, 31, v3
	v_lshrrev_b32_e32 v2, 22, v2
	v_add_u32_e32 v2, v3, v2
	v_ashrrev_i32_e32 v2, 10, v2
	v_mul_i32_i24_e32 v4, 0x400, v2
	v_sub_u32_e32 v3, v3, v4
	v_lshrrev_b32_e32 v4, 4, v3
	v_bitop3_b32 v4, v4, v3, 32 bitop3:0x6c
	v_ashrrev_i32_e32 v3, 31, v4
	v_lshrrev_b32_e32 v3, 26, v3
	v_add_u32_e32 v5, v4, v3
	v_lshlrev_b32_e32 v6, 3, v2
	s_ashr_i32 s65, s64, 31
	v_ashrrev_i32_e32 v3, 6, v5
	v_and_b32_e32 v6, -16, v6
	s_lshl_b64 s[0:1], s[64:65], 22
	v_readlane_b32 s10, v253, 7
	v_add_u32_e32 v6, v3, v6
	s_add_u32 s2, s10, s0
	v_and_b32_e32 v7, 3, v3
	s_mov_b32 s0, 0xfffe0
	v_lshrrev_b32_e32 v9, 2, v6
	v_lshlrev_b32_e32 v10, 1, v6
	v_and_b32_e32 v5, 0xc0, v5
	v_and_or_b32 v7, v6, s0, v7
	v_and_b32_e32 v9, 4, v9
	v_and_b32_e32 v10, 24, v10
	v_sub_u32_e32 v4, v4, v5
	v_or3_b32 v7, v7, v9, v10
	v_lshlrev_b32_e32 v9, 5, v2
	v_ashrrev_i16_sdwa v4, v233, sext(v4) dst_sel:DWORD dst_unused:UNUSED_PAD src0_sel:DWORD src1_sel:BYTE_0
	v_and_b32_e32 v9, 32, v9
	v_bfe_i32 v4, v4, 0, 16
	v_add_lshl_u32 v5, v9, v4, 1
	v_lshl_add_u32 v130, v7, 12, v5
	v_lshl_add_u32 v132, v6, 12, v5
	v_bfe_i32 v5, v8, 27, 1
	v_lshrrev_b32_e32 v5, 22, v5
	v_add_u32_e32 v5, v0, v5
	v_and_b32_e32 v5, 0xfffffc00, v5
	v_sub_u32_e32 v0, v0, v5
	v_lshrrev_b32_e32 v5, 4, v0
	v_bitop3_b32 v7, v5, v0, 32 bitop3:0x6c
	v_ashrrev_i32_e32 v0, 31, v0
	v_lshrrev_b32_e32 v0, 26, v0
	v_add_u32_e32 v0, v7, v0
	v_ashrrev_i32_e32 v5, 6, v0
	v_ashrrev_i32_e32 v0, 31, v8
	v_lshrrev_b32_e32 v0, 26, v0
	v_add_u32_e32 v0, v8, v0
	v_ashrrev_i32_e32 v6, 6, v0
	v_lshlrev_b32_e32 v0, 3, v6
	v_and_b32_e32 v0, -16, v0
	v_add_u32_e32 v9, v5, v0
	v_and_b32_e32 v0, 3, v5
	v_lshrrev_b32_e32 v10, 2, v9
	v_lshlrev_b32_e32 v11, 1, v9
	v_and_or_b32 v0, v9, s0, v0
	v_and_b32_e32 v10, 4, v10
	v_and_b32_e32 v11, 24, v11
	v_readlane_b32 s11, v253, 8
	v_or3_b32 v0, v0, v10, v11
	v_mul_i32_i24_e32 v11, 64, v5
	s_addc_u32 s15, s11, s1
	s_ashr_i32 s7, s6, 6
	v_sub_u32_e32 v7, v7, v11
	s_ashr_i32 s10, s6, 8
	s_lshl_b32 s22, s7, 10
	v_lshlrev_b32_e32 v10, 5, v6
	v_ashrrev_i16_sdwa v7, v233, sext(v7) dst_sel:DWORD dst_unused:UNUSED_PAD src0_sel:DWORD src1_sel:BYTE_0
	v_readlane_b32 s0, v254, 59
	v_and_b32_e32 v10, 32, v10
	v_bfe_i32 v7, v7, 0, 16
	v_readlane_b32 s1, v254, 60
	s_add_u32 s44, s2, s0
	v_add_lshl_u32 v10, v10, v7, 1
	s_addc_u32 s45, s15, s1
	s_add_i32 s23, s22, 0
	v_lshl_add_u32 v0, v0, 12, v10
	s_add_i32 m0, s23, 0x10000
	v_lshl_add_u32 v134, v9, 12, v10
	global_load_lds_dwordx4 v0, s[44:45]
	s_add_i32 m0, s23, 0x12000
	s_add_u32 s0, s44, 0x80000
	global_load_lds_dwordx4 v130, s[44:45]
	s_addc_u32 s1, s45, 0
	s_add_i32 m0, s23, 0x14000
	s_add_i32 s41, s23, 0x2000
	global_load_lds_dwordx4 v0, s[0:1]
	s_add_i32 m0, s23, 0x16000
	s_add_i32 s40, s23, 0x4000
	global_load_lds_dwordx4 v130, s[0:1]
	v_readlane_b32 s0, v254, 63
	s_mov_b32 m0, s23
	v_readlane_b32 s1, v255, 0
	s_add_i32 s48, s23, 0x6000
	s_cmp_eq_u32 s10, 1
	s_nop 2
	global_load_lds_dwordx4 v134, s[0:1]
	s_mov_b32 m0, s41
	s_nop 0
	global_load_lds_dwordx4 v132, s[0:1]
	v_readlane_b32 s0, v255, 1
	s_mov_b32 m0, s40
	v_readlane_b32 s1, v255, 2
	s_nop 4
	global_load_lds_dwordx4 v134, s[0:1]
	s_mov_b32 m0, s48
	s_nop 0
	global_load_lds_dwordx4 v132, s[0:1]
	s_cselect_b64 s[0:1], -1, 0
	s_cmp_lg_u32 s10, 1
	s_cbranch_scc1 .LBB0_40
	s_barrier

.LBB0_49:
	s_ashr_i32 s35, s34, 31
	s_lshl_b64 s[26:27], s[34:35], 20
	s_add_u32 s42, s16, s26
	s_addc_u32 s43, s17, s27
	s_and_b64 s[26:27], s[38:39], exec
	s_cselect_b32 s35, s43, s11
	s_cselect_b32 s52, s42, s10
	s_ashr_i32 s21, s20, 31
	s_lshl_b64 s[26:27], s[20:21], 20
	s_add_u32 s26, s2, s26
	s_addc_u32 s27, s15, s27
	s_and_b64 s[54:55], s[38:39], exec
	s_cselect_b32 s21, s27, s45
	s_cselect_b32 s53, s26, s44
	s_add_u32 vcc_lo, s10, 0x80080
	s_addc_u32 vcc_hi, s11, 0
	s_add_u32 s54, s44, 0x100
	v_mov_b32_e32 v2, 0
	s_addc_u32 s55, s45, 0
	s_mov_b32 s56, -2
	v_mov_b32_e32 v3, v2
	v_mov_b32_e32 v4, v2
	v_mov_b32_e32 v5, v2
	v_mov_b32_e32 v6, v2
	v_mov_b32_e32 v7, v2
	v_mov_b32_e32 v8, v2
	v_mov_b32_e32 v9, v2
	v_mov_b32_e32 v10, v2
	v_mov_b32_e32 v11, v2
	v_mov_b32_e32 v12, v2
	v_mov_b32_e32 v13, v2
	v_mov_b32_e32 v18, v2
	v_mov_b32_e32 v19, v2
	v_mov_b32_e32 v20, v2
	v_mov_b32_e32 v21, v2
	v_mov_b32_e32 v26, v2
	v_mov_b32_e32 v27, v2
	v_mov_b32_e32 v28, v2
	v_mov_b32_e32 v29, v2
	v_mov_b32_e32 v34, v2
	v_mov_b32_e32 v35, v2
	v_mov_b32_e32 v36, v2
	v_mov_b32_e32 v37, v2
	v_mov_b32_e32 v42, v2
	v_mov_b32_e32 v43, v2
	v_mov_b32_e32 v44, v2
	v_mov_b32_e32 v45, v2
	v_mov_b32_e32 v50, v2
	v_mov_b32_e32 v51, v2
	v_mov_b32_e32 v52, v2
	v_mov_b32_e32 v53, v2
	v_mov_b32_e32 v14, v2
	v_mov_b32_e32 v15, v2
	v_mov_b32_e32 v16, v2
	v_mov_b32_e32 v17, v2
	v_mov_b32_e32 v22, v2
	v_mov_b32_e32 v23, v2
	v_mov_b32_e32 v24, v2
	v_mov_b32_e32 v25, v2
	v_mov_b32_e32 v30, v2
	v_mov_b32_e32 v31, v2
	v_mov_b32_e32 v32, v2
	v_mov_b32_e32 v33, v2
	v_mov_b32_e32 v38, v2
	v_mov_b32_e32 v39, v2
	v_mov_b32_e32 v40, v2
	v_mov_b32_e32 v41, v2
	v_mov_b32_e32 v46, v2
	v_mov_b32_e32 v47, v2
	v_mov_b32_e32 v48, v2
	v_mov_b32_e32 v49, v2
	v_mov_b32_e32 v54, v2
	v_mov_b32_e32 v55, v2
	v_mov_b32_e32 v56, v2
	v_mov_b32_e32 v57, v2
	v_mov_b32_e32 v58, v2
	v_mov_b32_e32 v59, v2
	v_mov_b32_e32 v60, v2
	v_mov_b32_e32 v61, v2
	v_mov_b32_e32 v62, v2
	v_mov_b32_e32 v63, v2
	v_mov_b32_e32 v64, v2
	v_mov_b32_e32 v65, v2
	v_mov_b32_e32 v66, v2
	v_mov_b32_e32 v67, v2
	v_mov_b32_e32 v68, v2
	v_mov_b32_e32 v69, v2
	v_mov_b32_e32 v70, v2
	v_mov_b32_e32 v71, v2
	v_mov_b32_e32 v72, v2
	v_mov_b32_e32 v73, v2
	v_mov_b32_e32 v74, v2
	v_mov_b32_e32 v75, v2
	v_mov_b32_e32 v76, v2
	v_mov_b32_e32 v77, v2
	v_mov_b32_e32 v82, v2
	v_mov_b32_e32 v83, v2
	v_mov_b32_e32 v84, v2
	v_mov_b32_e32 v85, v2
	v_mov_b32_e32 v90, v2
	v_mov_b32_e32 v91, v2
	v_mov_b32_e32 v92, v2
	v_mov_b32_e32 v93, v2
	v_mov_b32_e32 v98, v2
	v_mov_b32_e32 v99, v2
	v_mov_b32_e32 v100, v2
	v_mov_b32_e32 v101, v2
	v_mov_b32_e32 v106, v2
	v_mov_b32_e32 v107, v2
	v_mov_b32_e32 v108, v2
	v_mov_b32_e32 v109, v2
	v_mov_b32_e32 v114, v2
	v_mov_b32_e32 v115, v2
	v_mov_b32_e32 v116, v2
	v_mov_b32_e32 v117, v2
	v_mov_b32_e32 v78, v2
	v_mov_b32_e32 v79, v2
	v_mov_b32_e32 v80, v2
	v_mov_b32_e32 v81, v2
	v_mov_b32_e32 v86, v2
	v_mov_b32_e32 v87, v2
	v_mov_b32_e32 v88, v2
	v_mov_b32_e32 v89, v2
	v_mov_b32_e32 v94, v2
	v_mov_b32_e32 v95, v2
	v_mov_b32_e32 v96, v2
	v_mov_b32_e32 v97, v2
	v_mov_b32_e32 v102, v2
	v_mov_b32_e32 v103, v2
	v_mov_b32_e32 v104, v2
	v_mov_b32_e32 v105, v2
	v_mov_b32_e32 v110, v2
	v_mov_b32_e32 v111, v2
	v_mov_b32_e32 v112, v2
	v_mov_b32_e32 v113, v2
	v_mov_b32_e32 v118, v2
	v_mov_b32_e32 v119, v2
	v_mov_b32_e32 v120, v2
	v_mov_b32_e32 v121, v2
	v_mov_b32_e32 v122, v2
	v_mov_b32_e32 v123, v2
	v_mov_b32_e32 v124, v2
	v_mov_b32_e32 v125, v2
	v_mov_b32_e32 v126, v2
	v_mov_b32_e32 v127, v2
	v_mov_b32_e32 v128, v2
	v_mov_b32_e32 v129, v2
	s_cmp_eq_u32 s100, 0
	s_cbranch_scc1 .LBB0_50
	s_add_u32 s10, vcc_lo, 0xfff80080
	s_addc_u32 s11, vcc_hi, -1
	s_add_i32 s57, 0, 0x10000
	s_cmp_eq_u32 s56, 28
	s_cselect_b32 s11, s35, s11
	s_cselect_b32 s10, s52, s10
	v_add_u32_e32 v140, s57, v143
	s_cselect_b32 s45, s21, s55
	s_cselect_b32 s44, s53, s54
	s_add_i32 s60, 0, 0x14000
	ds_read_b128 v[146:149], v140
	ds_read_b128 v[150:153], v140 offset:1024
	ds_read_b128 v[154:157], v140 offset:2048
	ds_read_b128 v[158:161], v140 offset:3072
	v_add_u32_e32 v140, s60, v143
	ds_read_b128 v[162:165], v140
	ds_read_b128 v[166:169], v140 offset:1024
	ds_read_b128 v[170:173], v140 offset:2048
	ds_read_b128 v[174:177], v140 offset:3072
	v_lshl_add_u64 v[140:141], vcc, 0, v[136:137]
	s_add_i32 m0, s23, 0xc000
	ds_read_b128 v[178:181], v145
	ds_read_b128 v[182:185], v145 offset:1024
	ds_read_b128 v[190:193], v145 offset:2048
	ds_read_b128 v[200:203], v145 offset:3072
	ds_read_b128 v[204:207], v145 offset:4096
	ds_read_b128 v[208:211], v145 offset:5120
	ds_read_b128 v[212:215], v145 offset:6144
	ds_read_b128 v[216:219], v145 offset:7168
	global_load_lds_dwordx4 v[140:141], off
	v_lshl_add_u64 v[140:141], vcc, 0, v[138:139]
	s_add_i32 m0, s23, 0xe000
	s_nop 0
	global_load_lds_dwordx4 v[140:141], off
	s_waitcnt vmcnt(24)
	s_waitcnt lgkmcnt(0)
	s_barrier
	s_setprio 1
	s_waitcnt lgkmcnt(0)
	v_mfma_f32_16x16x32_bf16 v[126:129], v[146:149], v[178:181], v[126:129]
	v_mfma_f32_16x16x32_bf16 v[122:125], v[154:157], v[178:181], v[122:125]
	v_mfma_f32_16x16x32_bf16 v[118:121], v[146:149], v[190:193], v[118:121]
	v_mfma_f32_16x16x32_bf16 v[110:113], v[154:157], v[190:193], v[110:113]
	v_mfma_f32_16x16x32_bf16 v[102:105], v[146:149], v[204:207], v[102:105]
	v_mfma_f32_16x16x32_bf16 v[94:97], v[154:157], v[204:207], v[94:97]
	v_mfma_f32_16x16x32_bf16 v[86:89], v[146:149], v[212:215], v[86:89]
	v_mfma_f32_16x16x32_bf16 v[78:81], v[154:157], v[212:215], v[78:81]
	v_mfma_f32_16x16x32_bf16 v[126:129], v[150:153], v[182:185], v[126:129]
	v_mfma_f32_16x16x32_bf16 v[122:125], v[158:161], v[182:185], v[122:125]
	v_mfma_f32_16x16x32_bf16 v[118:121], v[150:153], v[200:203], v[118:121]
	v_mfma_f32_16x16x32_bf16 v[110:113], v[158:161], v[200:203], v[110:113]
	v_mfma_f32_16x16x32_bf16 v[102:105], v[150:153], v[208:211], v[102:105]
	v_mfma_f32_16x16x32_bf16 v[94:97], v[158:161], v[208:211], v[94:97]
	v_mfma_f32_16x16x32_bf16 v[86:89], v[150:153], v[216:219], v[86:89]
	v_mfma_f32_16x16x32_bf16 v[78:81], v[158:161], v[216:219], v[78:81]
	s_setprio 0
	s_setprio 1
	v_mfma_f32_16x16x32_bf16 v[114:117], v[162:165], v[178:181], v[114:117]
	v_mfma_f32_16x16x32_bf16 v[106:109], v[170:173], v[178:181], v[106:109]
	v_mfma_f32_16x16x32_bf16 v[98:101], v[162:165], v[190:193], v[98:101]
	v_mfma_f32_16x16x32_bf16 v[90:93], v[170:173], v[190:193], v[90:93]
	v_mfma_f32_16x16x32_bf16 v[82:85], v[162:165], v[204:207], v[82:85]
	v_mfma_f32_16x16x32_bf16 v[74:77], v[170:173], v[204:207], v[74:77]
	v_mfma_f32_16x16x32_bf16 v[70:73], v[162:165], v[212:215], v[70:73]
	v_mfma_f32_16x16x32_bf16 v[66:69], v[170:173], v[212:215], v[66:69]
	v_mfma_f32_16x16x32_bf16 v[114:117], v[166:169], v[182:185], v[114:117]
	v_mfma_f32_16x16x32_bf16 v[106:109], v[174:177], v[182:185], v[106:109]
	v_mfma_f32_16x16x32_bf16 v[98:101], v[166:169], v[200:203], v[98:101]
	v_mfma_f32_16x16x32_bf16 v[90:93], v[174:177], v[200:203], v[90:93]
	v_mfma_f32_16x16x32_bf16 v[82:85], v[166:169], v[208:211], v[82:85]
	v_mfma_f32_16x16x32_bf16 v[74:77], v[174:177], v[208:211], v[74:77]
	v_mfma_f32_16x16x32_bf16 v[70:73], v[166:169], v[216:219], v[70:73]
	v_mfma_f32_16x16x32_bf16 v[66:69], v[174:177], v[216:219], v[66:69]
	s_setprio 0
	s_barrier
	s_add_i32 s57, s57, s22
	v_lshl_add_u64 v[140:141], s[44:45], 0, v[0:1]
	s_mov_b32 m0, s57
	ds_read_b128 v[178:181], v145 offset:16384
	ds_read_b128 v[182:185], v145 offset:17408
	ds_read_b128 v[190:193], v145 offset:18432
	ds_read_b128 v[200:203], v145 offset:19456
	ds_read_b128 v[204:207], v145 offset:20480
	ds_read_b128 v[208:211], v145 offset:21504
	ds_read_b128 v[212:215], v145 offset:22528
	ds_read_b128 v[216:219], v145 offset:23552
	global_load_lds_dwordx4 v[140:141], off
	s_add_i32 m0, s57, 0x2000
	s_add_u32 s58, s44, 0x80000
	v_lshl_add_u64 v[220:221], s[44:45], 0, v[130:131]
	s_addc_u32 s59, s45, 0
	s_add_i32 s57, s60, s22
	global_load_lds_dwordx4 v[220:221], off
	v_lshl_add_u64 v[222:223], s[58:59], 0, v[0:1]
	s_mov_b32 m0, s57
	v_lshl_add_u64 v[224:225], s[10:11], 0, v[132:133]
	global_load_lds_dwordx4 v[222:223], off
	v_lshl_add_u64 v[222:223], s[58:59], 0, v[130:131]
	s_add_i32 m0, s57, 0x2000
	s_nop 0
	global_load_lds_dwordx4 v[222:223], off
	v_lshl_add_u64 v[222:223], s[10:11], 0, v[134:135]
	s_mov_b32 m0, s23
	s_nop 0
	global_load_lds_dwordx4 v[222:223], off
	s_mov_b32 m0, s41
	s_nop 0
	global_load_lds_dwordx4 v[224:225], off
	s_waitcnt vmcnt(24)
	s_waitcnt lgkmcnt(0)
	s_barrier
	s_setprio 1
	s_waitcnt lgkmcnt(0)
	v_mfma_f32_16x16x32_bf16 v[62:65], v[146:149], v[178:181], v[62:65]
	v_mfma_f32_16x16x32_bf16 v[58:61], v[154:157], v[178:181], v[58:61]
	v_mfma_f32_16x16x32_bf16 v[54:57], v[146:149], v[190:193], v[54:57]
	v_mfma_f32_16x16x32_bf16 v[46:49], v[154:157], v[190:193], v[46:49]
	v_mfma_f32_16x16x32_bf16 v[38:41], v[146:149], v[204:207], v[38:41]
	v_mfma_f32_16x16x32_bf16 v[30:33], v[154:157], v[204:207], v[30:33]
	v_mfma_f32_16x16x32_bf16 v[22:25], v[146:149], v[212:215], v[22:25]
	v_mfma_f32_16x16x32_bf16 v[14:17], v[154:157], v[212:215], v[14:17]
	v_mfma_f32_16x16x32_bf16 v[62:65], v[150:153], v[182:185], v[62:65]
	v_mfma_f32_16x16x32_bf16 v[58:61], v[158:161], v[182:185], v[58:61]
	v_mfma_f32_16x16x32_bf16 v[54:57], v[150:153], v[200:203], v[54:57]
	v_mfma_f32_16x16x32_bf16 v[46:49], v[158:161], v[200:203], v[46:49]
	v_mfma_f32_16x16x32_bf16 v[38:41], v[150:153], v[208:211], v[38:41]
	v_mfma_f32_16x16x32_bf16 v[30:33], v[158:161], v[208:211], v[30:33]
	v_mfma_f32_16x16x32_bf16 v[22:25], v[150:153], v[216:219], v[22:25]
	v_mfma_f32_16x16x32_bf16 v[14:17], v[158:161], v[216:219], v[14:17]
	s_setprio 0
	s_setprio 1
	v_mfma_f32_16x16x32_bf16 v[50:53], v[162:165], v[178:181], v[50:53]
	v_mfma_f32_16x16x32_bf16 v[42:45], v[170:173], v[178:181], v[42:45]
	v_mfma_f32_16x16x32_bf16 v[34:37], v[162:165], v[190:193], v[34:37]
	v_mfma_f32_16x16x32_bf16 v[26:29], v[170:173], v[190:193], v[26:29]
	v_mfma_f32_16x16x32_bf16 v[18:21], v[162:165], v[204:207], v[18:21]
	v_mfma_f32_16x16x32_bf16 v[10:13], v[170:173], v[204:207], v[10:13]
	v_mfma_f32_16x16x32_bf16 v[6:9], v[162:165], v[212:215], v[6:9]
	v_mfma_f32_16x16x32_bf16 v[2:5], v[170:173], v[212:215], v[2:5]
	v_mfma_f32_16x16x32_bf16 v[50:53], v[166:169], v[182:185], v[50:53]
	v_mfma_f32_16x16x32_bf16 v[42:45], v[174:177], v[182:185], v[42:45]
	v_mfma_f32_16x16x32_bf16 v[34:37], v[166:169], v[200:203], v[34:37]
	v_mfma_f32_16x16x32_bf16 v[26:29], v[174:177], v[200:203], v[26:29]
	v_mfma_f32_16x16x32_bf16 v[18:21], v[166:169], v[208:211], v[18:21]
	v_mfma_f32_16x16x32_bf16 v[10:13], v[174:177], v[208:211], v[10:13]
	v_mfma_f32_16x16x32_bf16 v[6:9], v[166:169], v[216:219], v[6:9]
	v_mfma_f32_16x16x32_bf16 v[2:5], v[174:177], v[216:219], v[2:5]
	s_setprio 0
	s_barrier
	s_branch .Lg50_mid

.Lg50_mid:
	s_add_i32 s57, 0, 0x18000
	s_add_i32 s58, 0, 0x1c000
	v_add_u32_e32 v158, s57, v143
	v_add_u32_e32 v174, s58, v143
	ds_read_b128 v[146:149], v158
	ds_read_b128 v[150:153], v158 offset:1024
	ds_read_b128 v[154:157], v158 offset:2048
	ds_read_b128 v[158:161], v158 offset:3072
	ds_read_b128 v[162:165], v174
	ds_read_b128 v[166:169], v174 offset:1024
	ds_read_b128 v[170:173], v174 offset:2048
	ds_read_b128 v[174:177], v174 offset:3072
	s_add_u32 s10, s10, 0x80000
	s_addc_u32 s11, s11, 0
	s_mov_b32 m0, s40
	v_lshl_add_u64 v[226:227], s[10:11], 0, v[134:135]
	ds_read_b128 v[178:181], v145 offset:32768
	ds_read_b128 v[182:185], v145 offset:33792
	ds_read_b128 v[190:193], v145 offset:34816
	ds_read_b128 v[200:203], v145 offset:35840
	ds_read_b128 v[204:207], v145 offset:36864
	ds_read_b128 v[208:211], v145 offset:37888
	ds_read_b128 v[212:215], v145 offset:38912
	ds_read_b128 v[216:219], v145 offset:39936
	global_load_lds_dwordx4 v[226:227], off
	v_lshl_add_u64 v[226:227], s[10:11], 0, v[132:133]
	s_mov_b32 m0, s48
	s_nop 0
	global_load_lds_dwordx4 v[226:227], off
	s_waitcnt vmcnt(8)
	s_waitcnt lgkmcnt(0)
	s_barrier
	s_setprio 1
	s_waitcnt lgkmcnt(0)
	v_mfma_f32_16x16x32_bf16 v[126:129], v[146:149], v[178:181], v[126:129]
	v_mfma_f32_16x16x32_bf16 v[122:125], v[154:157], v[178:181], v[122:125]
	v_mfma_f32_16x16x32_bf16 v[118:121], v[146:149], v[190:193], v[118:121]
	v_mfma_f32_16x16x32_bf16 v[110:113], v[154:157], v[190:193], v[110:113]
	v_mfma_f32_16x16x32_bf16 v[102:105], v[146:149], v[204:207], v[102:105]
	v_mfma_f32_16x16x32_bf16 v[94:97], v[154:157], v[204:207], v[94:97]
	v_mfma_f32_16x16x32_bf16 v[86:89], v[146:149], v[212:215], v[86:89]
	v_mfma_f32_16x16x32_bf16 v[78:81], v[154:157], v[212:215], v[78:81]
	v_mfma_f32_16x16x32_bf16 v[126:129], v[150:153], v[182:185], v[126:129]
	v_mfma_f32_16x16x32_bf16 v[122:125], v[158:161], v[182:185], v[122:125]
	v_mfma_f32_16x16x32_bf16 v[118:121], v[150:153], v[200:203], v[118:121]
	v_mfma_f32_16x16x32_bf16 v[110:113], v[158:161], v[200:203], v[110:113]
	v_mfma_f32_16x16x32_bf16 v[102:105], v[150:153], v[208:211], v[102:105]
	v_mfma_f32_16x16x32_bf16 v[94:97], v[158:161], v[208:211], v[94:97]
	v_mfma_f32_16x16x32_bf16 v[86:89], v[150:153], v[216:219], v[86:89]
	v_mfma_f32_16x16x32_bf16 v[78:81], v[158:161], v[216:219], v[78:81]
	s_setprio 0
	s_setprio 1
	v_mfma_f32_16x16x32_bf16 v[114:117], v[162:165], v[178:181], v[114:117]
	v_mfma_f32_16x16x32_bf16 v[106:109], v[170:173], v[178:181], v[106:109]
	v_mfma_f32_16x16x32_bf16 v[98:101], v[162:165], v[190:193], v[98:101]
	v_mfma_f32_16x16x32_bf16 v[90:93], v[170:173], v[190:193], v[90:93]
	v_mfma_f32_16x16x32_bf16 v[82:85], v[162:165], v[204:207], v[82:85]
	v_mfma_f32_16x16x32_bf16 v[74:77], v[170:173], v[204:207], v[74:77]
	v_mfma_f32_16x16x32_bf16 v[70:73], v[162:165], v[212:215], v[70:73]
	v_mfma_f32_16x16x32_bf16 v[66:69], v[170:173], v[212:215], v[66:69]
	v_mfma_f32_16x16x32_bf16 v[114:117], v[166:169], v[182:185], v[114:117]
	v_mfma_f32_16x16x32_bf16 v[106:109], v[174:177], v[182:185], v[106:109]
	v_mfma_f32_16x16x32_bf16 v[98:101], v[166:169], v[200:203], v[98:101]
	v_mfma_f32_16x16x32_bf16 v[90:93], v[174:177], v[200:203], v[90:93]
	v_mfma_f32_16x16x32_bf16 v[82:85], v[166:169], v[208:211], v[82:85]
	v_mfma_f32_16x16x32_bf16 v[74:77], v[174:177], v[208:211], v[74:77]
	v_mfma_f32_16x16x32_bf16 v[70:73], v[166:169], v[216:219], v[70:73]
	v_mfma_f32_16x16x32_bf16 v[66:69], v[174:177], v[216:219], v[66:69]
	s_setprio 0
	s_barrier
	s_add_i32 s10, s57, s22
	v_lshl_add_u64 v[140:141], v[140:141], 0, s[46:47]
	s_mov_b32 m0, s10
	ds_read_b128 v[178:181], v145 offset:49152
	ds_read_b128 v[182:185], v145 offset:50176
	ds_read_b128 v[190:193], v145 offset:51200
	ds_read_b128 v[200:203], v145 offset:52224
	ds_read_b128 v[204:207], v145 offset:53248
	ds_read_b128 v[208:211], v145 offset:54272
	ds_read_b128 v[212:215], v145 offset:55296
	ds_read_b128 v[216:219], v145 offset:56320
	global_load_lds_dwordx4 v[140:141], off
	s_add_i32 m0, s10, 0x2000
	s_add_u32 s10, s44, 0x80080
	v_lshl_add_u64 v[140:141], v[220:221], 0, s[46:47]
	s_addc_u32 s11, s45, 0
	s_add_i32 s44, s58, s22
	global_load_lds_dwordx4 v[140:141], off
	v_lshl_add_u64 v[140:141], s[10:11], 0, v[0:1]
	s_mov_b32 m0, s44
	s_nop 0
	global_load_lds_dwordx4 v[140:141], off
	v_lshl_add_u64 v[140:141], s[10:11], 0, v[130:131]
	s_add_i32 m0, s44, 0x2000
	s_nop 0
	global_load_lds_dwordx4 v[140:141], off
	v_lshl_add_u64 v[140:141], v[222:223], 0, s[46:47]
	s_mov_b32 m0, s95
	s_nop 0
	global_load_lds_dwordx4 v[140:141], off
	v_lshl_add_u64 v[140:141], v[224:225], 0, s[46:47]
	s_mov_b32 m0, s31
	s_nop 0
	global_load_lds_dwordx4 v[140:141], off
	s_waitcnt vmcnt(8)
	s_waitcnt lgkmcnt(0)
	s_barrier
	s_setprio 1
	s_waitcnt lgkmcnt(0)
	v_mfma_f32_16x16x32_bf16 v[62:65], v[146:149], v[178:181], v[62:65]
	v_mfma_f32_16x16x32_bf16 v[58:61], v[154:157], v[178:181], v[58:61]
	v_mfma_f32_16x16x32_bf16 v[54:57], v[146:149], v[190:193], v[54:57]
	v_mfma_f32_16x16x32_bf16 v[46:49], v[154:157], v[190:193], v[46:49]
	v_mfma_f32_16x16x32_bf16 v[38:41], v[146:149], v[204:207], v[38:41]
	v_mfma_f32_16x16x32_bf16 v[30:33], v[154:157], v[204:207], v[30:33]
	v_mfma_f32_16x16x32_bf16 v[22:25], v[146:149], v[212:215], v[22:25]
	v_mfma_f32_16x16x32_bf16 v[14:17], v[154:157], v[212:215], v[14:17]
	v_mfma_f32_16x16x32_bf16 v[62:65], v[150:153], v[182:185], v[62:65]
	v_mfma_f32_16x16x32_bf16 v[58:61], v[158:161], v[182:185], v[58:61]
	v_mfma_f32_16x16x32_bf16 v[54:57], v[150:153], v[200:203], v[54:57]
	v_mfma_f32_16x16x32_bf16 v[46:49], v[158:161], v[200:203], v[46:49]
	v_mfma_f32_16x16x32_bf16 v[38:41], v[150:153], v[208:211], v[38:41]
	v_mfma_f32_16x16x32_bf16 v[30:33], v[158:161], v[208:211], v[30:33]
	v_mfma_f32_16x16x32_bf16 v[22:25], v[150:153], v[216:219], v[22:25]
	v_mfma_f32_16x16x32_bf16 v[14:17], v[158:161], v[216:219], v[14:17]
	s_setprio 0
	s_setprio 1
	v_mfma_f32_16x16x32_bf16 v[50:53], v[162:165], v[178:181], v[50:53]
	v_mfma_f32_16x16x32_bf16 v[42:45], v[170:173], v[178:181], v[42:45]
	v_mfma_f32_16x16x32_bf16 v[34:37], v[162:165], v[190:193], v[34:37]
	v_mfma_f32_16x16x32_bf16 v[26:29], v[170:173], v[190:193], v[26:29]
	v_mfma_f32_16x16x32_bf16 v[18:21], v[162:165], v[204:207], v[18:21]
	v_mfma_f32_16x16x32_bf16 v[10:13], v[170:173], v[204:207], v[10:13]
	v_mfma_f32_16x16x32_bf16 v[6:9], v[162:165], v[212:215], v[6:9]
	v_mfma_f32_16x16x32_bf16 v[2:5], v[170:173], v[212:215], v[2:5]
	v_mfma_f32_16x16x32_bf16 v[50:53], v[166:169], v[182:185], v[50:53]
	v_mfma_f32_16x16x32_bf16 v[42:45], v[174:177], v[182:185], v[42:45]
	v_mfma_f32_16x16x32_bf16 v[34:37], v[166:169], v[200:203], v[34:37]
	v_mfma_f32_16x16x32_bf16 v[26:29], v[174:177], v[200:203], v[26:29]
	v_mfma_f32_16x16x32_bf16 v[18:21], v[166:169], v[208:211], v[18:21]
	v_mfma_f32_16x16x32_bf16 v[10:13], v[174:177], v[208:211], v[10:13]
	v_mfma_f32_16x16x32_bf16 v[6:9], v[166:169], v[216:219], v[6:9]
	v_mfma_f32_16x16x32_bf16 v[2:5], v[174:177], v[216:219], v[2:5]
	s_setprio 0
	s_barrier
	s_add_i32 s56, s56, 2
	s_add_u32 vcc_lo, vcc_lo, 0x100
	s_addc_u32 vcc_hi, vcc_hi, 0
	s_add_u32 s54, s54, 0x100
	s_addc_u32 s55, s55, 0
	s_cmp_gt_u32 s56, 29
	s_cbranch_scc0 .LBB0_50
	s_and_b64 vcc, exec, s[18:19]
	s_cbranch_vccz .LBB0_53
	s_barrier
.LBB0_53:
	s_mov_b32 s100, 1
	v_lshl_add_u32 v146, s7, 8, v142
	v_lshl_or_b32 v140, s6, 8, v144
	v_ashrrev_i32_e32 v141, 31, v140
	v_ashrrev_i32_e32 v147, 31, v146
	v_lshl_add_u64 v[148:149], v[140:141], 1, s[12:13]
	v_lshlrev_b64 v[140:141], 11, v[146:147]
	v_lshl_add_u64 v[140:141], v[148:149], 0, v[140:141]
	v_add_f32_e32 v147, 0, v124
	v_add_f32_e32 v124, 0, v122
	v_cvt_pk_bf16_f32 v122, v126, v127
	v_add_f32_e32 v150, 0, v123
	v_cvt_pk_bf16_f32 v123, v128, v129
	v_cvt_pk_bf16_f32 v124, v124, v150
	v_cvt_pk_bf16_f32 v125, v147, v125
	global_store_dwordx4 v[140:141], v[122:125], off
	s_nop 1
	v_add_f32_e32 v122, 0, v108
	v_add_f32_e32 v108, 0, v106
	v_cvt_pk_bf16_f32 v106, v114, v115
	v_add_f32_e32 v123, 0, v107
	v_cvt_pk_bf16_f32 v107, v116, v117
	v_cvt_pk_bf16_f32 v108, v108, v123
	v_cvt_pk_bf16_f32 v109, v122, v109
	global_store_dwordx4 v[140:141], v[106:109], off offset:256
	s_nop 1
	v_or_b32_e32 v106, 16, v146
	v_ashrrev_i32_e32 v107, 31, v106
	v_lshlrev_b64 v[106:107], 11, v[106:107]
	v_lshl_add_u64 v[114:115], v[148:149], 0, v[106:107]
	v_add_f32_e32 v106, 0, v118
	v_add_f32_e32 v107, 0, v120
	v_add_f32_e32 v108, 0, v121
	v_add_f32_e32 v109, 0, v119
	v_cvt_pk_bf16_f32 v106, v106, v109
	v_cvt_pk_bf16_f32 v107, v107, v108
	v_cvt_pk_bf16_f32 v108, v110, v111
	v_cvt_pk_bf16_f32 v109, v112, v113
	global_store_dwordx4 v[114:115], v[106:109], off
	s_nop 1
	v_add_f32_e32 v106, 0, v92
	v_add_f32_e32 v92, 0, v90
	v_cvt_pk_bf16_f32 v90, v98, v99
	v_add_f32_e32 v107, 0, v91
	v_cvt_pk_bf16_f32 v91, v100, v101
	v_cvt_pk_bf16_f32 v92, v92, v107
	v_cvt_pk_bf16_f32 v93, v106, v93
	global_store_dwordx4 v[114:115], v[90:93], off offset:256
	s_nop 1
	v_or_b32_e32 v90, 32, v146
	v_ashrrev_i32_e32 v91, 31, v90
	v_lshlrev_b64 v[90:91], 11, v[90:91]
	v_lshl_add_u64 v[98:99], v[148:149], 0, v[90:91]
	v_add_f32_e32 v90, 0, v102
	v_add_f32_e32 v91, 0, v104
	v_add_f32_e32 v92, 0, v105
	v_add_f32_e32 v93, 0, v103
	v_cvt_pk_bf16_f32 v90, v90, v93
	v_cvt_pk_bf16_f32 v91, v91, v92
	v_cvt_pk_bf16_f32 v92, v94, v95
	v_cvt_pk_bf16_f32 v93, v96, v97
	global_store_dwordx4 v[98:99], v[90:93], off
	s_nop 1
	v_add_f32_e32 v90, 0, v76
	v_add_f32_e32 v76, 0, v74
	v_cvt_pk_bf16_f32 v74, v82, v83
	v_add_f32_e32 v91, 0, v75
	v_cvt_pk_bf16_f32 v75, v84, v85
	v_cvt_pk_bf16_f32 v76, v76, v91
	v_cvt_pk_bf16_f32 v77, v90, v77
	global_store_dwordx4 v[98:99], v[74:77], off offset:256
	s_nop 1
	v_or_b32_e32 v74, 48, v146
	v_ashrrev_i32_e32 v75, 31, v74
	v_lshlrev_b64 v[74:75], 11, v[74:75]
	v_lshl_add_u64 v[82:83], v[148:149], 0, v[74:75]
	v_add_f32_e32 v74, 0, v86
	v_add_f32_e32 v75, 0, v88
	v_add_f32_e32 v76, 0, v89
	v_add_f32_e32 v77, 0, v87
	v_cvt_pk_bf16_f32 v74, v74, v77
	v_cvt_pk_bf16_f32 v75, v75, v76
	v_cvt_pk_bf16_f32 v76, v78, v79
	v_cvt_pk_bf16_f32 v77, v80, v81
	global_store_dwordx4 v[82:83], v[74:77], off
	s_nop 1
	v_add_f32_e32 v74, 0, v68
	v_add_f32_e32 v68, 0, v66
	v_add_f32_e32 v75, 0, v67
	v_cvt_pk_bf16_f32 v66, v70, v71
	v_cvt_pk_bf16_f32 v67, v72, v73
	v_cvt_pk_bf16_f32 v68, v68, v75
	s_mov_b32 s6, 0x40000
	v_cvt_pk_bf16_f32 v69, v74, v69
	global_store_dwordx4 v[82:83], v[66:69], off offset:256
	s_nop 1
	v_add_f32_e32 v68, 0, v60
	v_add_f32_e32 v60, 0, v58
	v_cvt_pk_bf16_f32 v58, v62, v63
	v_add_co_u32_e32 v62, vcc, s6, v140
	s_nop 0
	v_addc_co_u32_e32 v63, vcc, 0, v141, vcc
	v_add_f32_e32 v69, 0, v59
	v_cvt_pk_bf16_f32 v59, v64, v65
	v_cvt_pk_bf16_f32 v60, v60, v69
	v_cvt_pk_bf16_f32 v61, v68, v61
	global_store_dwordx4 v[62:63], v[58:61], off
	s_nop 1
	v_lshl_add_u64 v[66:67], v[140:141], 0, s[36:37]
	v_add_f32_e32 v58, 0, v44
	v_add_f32_e32 v44, 0, v42
	v_add_f32_e32 v59, 0, v43
	v_cvt_pk_bf16_f32 v42, v50, v51
	v_cvt_pk_bf16_f32 v43, v52, v53
	v_cvt_pk_bf16_f32 v44, v44, v59
	s_mov_b64 s[6:7], 0x48000
	v_cvt_pk_bf16_f32 v45, v58, v45
	global_store_dwordx4 v[66:67], v[42:45], off offset:256
	s_nop 1
	v_lshl_add_u64 v[50:51], v[140:141], 0, s[6:7]
	v_add_f32_e32 v43, 0, v56
	v_add_f32_e32 v44, 0, v57
	v_add_f32_e32 v42, 0, v54
	s_mov_b32 s6, 0x48000
	v_add_f32_e32 v45, 0, v55
	v_cvt_pk_bf16_f32 v42, v42, v45
	v_cvt_pk_bf16_f32 v43, v43, v44
	v_cvt_pk_bf16_f32 v44, v46, v47
	v_add_co_u32_e32 v46, vcc, s6, v140
	s_nop 0
	v_addc_co_u32_e32 v47, vcc, 0, v141, vcc
	v_cvt_pk_bf16_f32 v45, v48, v49
	global_store_dwordx4 v[46:47], v[42:45], off
	s_nop 1
	v_add_f32_e32 v42, 0, v28
	v_add_f32_e32 v28, 0, v26
	v_add_f32_e32 v43, 0, v27
	v_cvt_pk_bf16_f32 v26, v34, v35
	v_cvt_pk_bf16_f32 v27, v36, v37
	v_cvt_pk_bf16_f32 v28, v28, v43
	s_mov_b64 s[6:7], 0x50000
	v_cvt_pk_bf16_f32 v29, v42, v29
	global_store_dwordx4 v[50:51], v[26:29], off offset:256
	s_nop 1
	v_lshl_add_u64 v[34:35], v[140:141], 0, s[6:7]
	v_add_f32_e32 v27, 0, v40
	v_add_f32_e32 v28, 0, v41
	v_add_f32_e32 v26, 0, v38
	s_mov_b32 s6, 0x50000
	v_add_f32_e32 v29, 0, v39
	v_cvt_pk_bf16_f32 v26, v26, v29
	v_cvt_pk_bf16_f32 v27, v27, v28
	v_cvt_pk_bf16_f32 v28, v30, v31
	v_add_co_u32_e32 v30, vcc, s6, v140
	s_nop 0
	v_addc_co_u32_e32 v31, vcc, 0, v141, vcc
	v_cvt_pk_bf16_f32 v29, v32, v33
	global_store_dwordx4 v[30:31], v[26:29], off
	s_nop 1
	v_add_f32_e32 v26, 0, v12
	v_add_f32_e32 v12, 0, v10
	v_add_f32_e32 v27, 0, v11
	v_cvt_pk_bf16_f32 v10, v18, v19
	v_cvt_pk_bf16_f32 v11, v20, v21
	v_cvt_pk_bf16_f32 v12, v12, v27
	s_mov_b64 s[6:7], 0x58000
	v_cvt_pk_bf16_f32 v13, v26, v13
	global_store_dwordx4 v[34:35], v[10:13], off offset:256
	s_nop 1
	v_lshl_add_u64 v[18:19], v[140:141], 0, s[6:7]
	v_add_f32_e32 v11, 0, v24
	v_add_f32_e32 v12, 0, v25
	v_add_f32_e32 v10, 0, v22
	s_mov_b32 s6, 0x58000
	v_add_f32_e32 v13, 0, v23
	v_cvt_pk_bf16_f32 v10, v10, v13
	v_cvt_pk_bf16_f32 v11, v11, v12
	v_cvt_pk_bf16_f32 v12, v14, v15
	v_add_co_u32_e32 v14, vcc, s6, v140
	s_nop 0
	v_addc_co_u32_e32 v15, vcc, 0, v141, vcc
	v_cvt_pk_bf16_f32 v13, v16, v17
	global_store_dwordx4 v[14:15], v[10:13], off
	s_nop 1
	s_andn2_b64 vcc, exec, s[38:39]
	v_add_f32_e32 v10, 0, v4
	v_add_f32_e32 v4, 0, v2
	s_mov_b64 s[10:11], -1
	v_add_f32_e32 v11, 0, v3
	v_cvt_pk_bf16_f32 v2, v6, v7
	v_cvt_pk_bf16_f32 v3, v8, v9
	v_cvt_pk_bf16_f32 v4, v4, v11
	v_cvt_pk_bf16_f32 v5, v10, v5
	global_store_dwordx4 v[18:19], v[2:5], off offset:256
	s_nop 1
	s_cbranch_vccnz .LBB0_42
	s_andn2_b64 vcc, exec, s[0:1]
	s_cbranch_vccnz .LBB0_41
	s_barrier
	s_branch .LBB0_41

.LBB0_58:
	s_andn2_b64 vcc, exec, s[0:1]
	s_cbranch_vccnz .LBB0_147
	s_cmp_eq_u32 s63, 1
	s_mov_b64 s[0:1], -1
	s_cbranch_scc1 .LBB0_81
	v_readlane_b32 s0, v253, 44
	v_mov_b32_e32 v2, v186
	v_readlane_b32 s1, v253, 45
	s_andn2_b64 vcc, exec, s[0:1]
	v_readfirstlane_b32 s6, v2
	s_cbranch_vccnz .LBB0_80
	s_mov_b32 s100, 0
	v_lshlrev_b32_e32 v0, 4, v2
	v_add_u32_e32 v4, 0x2000, v0
	v_ashrrev_i32_e32 v3, 31, v4
	v_lshrrev_b32_e32 v3, 22, v3
	v_add_u32_e32 v3, v4, v3
	v_ashrrev_i32_e32 v3, 10, v3
	v_mul_i32_i24_e32 v5, 0x400, v3
	v_sub_u32_e32 v4, v4, v5
	v_lshrrev_b32_e32 v5, 4, v4
	v_bitop3_b32 v5, v5, v4, 32 bitop3:0x6c
	v_ashrrev_i32_e32 v4, 31, v5
	v_lshrrev_b32_e32 v4, 26, v4
	v_add_u32_e32 v6, v5, v4
	v_lshlrev_b32_e32 v7, 3, v3
	s_ashr_i32 s65, s64, 31
	v_ashrrev_i32_e32 v4, 6, v6
	v_and_b32_e32 v7, -16, v7
	s_lshl_b64 s[0:1], s[64:65], 23
	v_add_u32_e32 v7, v4, v7
	s_add_u32 s2, s90, s0
	v_and_b32_e32 v8, 3, v4
	s_mov_b32 s0, 0x1fffe0
	v_lshrrev_b32_e32 v9, 2, v7
	v_lshlrev_b32_e32 v10, 1, v7
	v_and_b32_e32 v6, 0xc0, v6
	v_and_or_b32 v8, v7, s0, v8
	v_and_b32_e32 v9, 4, v9
	v_and_b32_e32 v10, 24, v10
	v_sub_u32_e32 v5, v5, v6
	v_or3_b32 v8, v8, v9, v10
	v_lshlrev_b32_e32 v9, 5, v3
	v_ashrrev_i16_sdwa v5, v233, sext(v5) dst_sel:DWORD dst_unused:UNUSED_PAD src0_sel:DWORD src1_sel:BYTE_0
	v_and_b32_e32 v9, 32, v9
	v_bfe_i32 v5, v5, 0, 16
	v_add_lshl_u32 v6, v9, v5, 1
	v_lshl_add_u32 v130, v8, 11, v6
	v_lshl_add_u32 v132, v7, 11, v6
	v_bfe_i32 v6, v2, 27, 1
	v_lshrrev_b32_e32 v6, 22, v6
	v_add_u32_e32 v6, v0, v6
	v_and_b32_e32 v6, 0xfffffc00, v6
	v_sub_u32_e32 v0, v0, v6
	v_lshrrev_b32_e32 v6, 4, v0
	v_bitop3_b32 v8, v6, v0, 32 bitop3:0x6c
	v_ashrrev_i32_e32 v0, 31, v0
	v_lshrrev_b32_e32 v0, 26, v0
	v_add_u32_e32 v0, v8, v0
	v_ashrrev_i32_e32 v6, 6, v0
	v_ashrrev_i32_e32 v0, 31, v2
	v_lshrrev_b32_e32 v0, 26, v0
	v_add_u32_e32 v0, v2, v0
	v_ashrrev_i32_e32 v7, 6, v0
	v_lshlrev_b32_e32 v0, 3, v7
	v_and_b32_e32 v0, -16, v0
	v_add_u32_e32 v9, v6, v0
	v_and_b32_e32 v0, 3, v6
	v_lshrrev_b32_e32 v10, 2, v9
	v_lshlrev_b32_e32 v11, 1, v9
	v_and_or_b32 v0, v9, s0, v0
	v_and_b32_e32 v10, 4, v10
	v_and_b32_e32 v11, 24, v11
	v_or3_b32 v0, v0, v10, v11
	v_mul_i32_i24_e32 v11, 64, v6
	s_addc_u32 s15, s91, s1
	s_ashr_i32 s10, s6, 6
	v_sub_u32_e32 v8, v8, v11
	s_ashr_i32 s7, s6, 8
	s_lshl_b32 s22, s10, 10
	v_lshlrev_b32_e32 v10, 5, v7
	v_ashrrev_i16_sdwa v8, v233, sext(v8) dst_sel:DWORD dst_unused:UNUSED_PAD src0_sel:DWORD src1_sel:BYTE_0
	v_readlane_b32 s0, v255, 4
	v_and_b32_e32 v10, 32, v10
	v_bfe_i32 v8, v8, 0, 16
	v_readlane_b32 s1, v255, 5
	s_add_u32 s26, s2, s0
	v_add_lshl_u32 v10, v10, v8, 1
	s_addc_u32 s27, s15, s1
	s_add_i32 s23, s22, 0
	v_lshl_add_u32 v0, v0, 11, v10
	s_add_i32 m0, s23, 0x10000
	v_lshl_add_u32 v134, v9, 11, v10
	global_load_lds_dwordx4 v0, s[26:27]
	s_add_i32 m0, s23, 0x12000
	s_add_u32 s0, s26, 0x40000
	global_load_lds_dwordx4 v130, s[26:27]
	s_addc_u32 s1, s27, 0
	s_add_i32 m0, s23, 0x14000
	s_add_i32 s40, s23, 0x2000
	global_load_lds_dwordx4 v0, s[0:1]
	s_add_i32 m0, s23, 0x16000
	s_add_i32 s41, s23, 0x4000
	global_load_lds_dwordx4 v130, s[0:1]
	v_readlane_b32 s0, v255, 10
	s_mov_b32 m0, s23
	v_readlane_b32 s1, v255, 11
	s_add_i32 s48, s23, 0x6000
	s_cmp_eq_u32 s7, 1
	s_nop 2
	global_load_lds_dwordx4 v134, s[0:1]
	s_mov_b32 m0, s40
	s_nop 0
	global_load_lds_dwordx4 v132, s[0:1]
	v_readlane_b32 s0, v255, 12
	s_mov_b32 m0, s41
	v_readlane_b32 s1, v255, 13
	s_nop 4
	global_load_lds_dwordx4 v134, s[0:1]
	s_mov_b32 m0, s48
	s_nop 0
	global_load_lds_dwordx4 v132, s[0:1]
	s_cselect_b64 s[0:1], -1, 0
	s_cmp_lg_u32 s7, 1
	s_cbranch_scc1 .LBB0_63
	s_barrier

.LBB0_72:
	s_ashr_i32 s35, s34, 31
	s_lshl_b64 s[42:43], s[34:35], 19
	v_readlane_b32 s44, v255, 8
	v_readlane_b32 s45, v255, 9
	s_add_u32 s42, s44, s42
	s_addc_u32 s43, s45, s43
	s_and_b64 s[44:45], s[38:39], exec
	s_cselect_b32 s35, s43, s11
	s_cselect_b32 s52, s42, s10
	s_ashr_i32 s21, s20, 31
	s_lshl_b64 s[44:45], s[20:21], 19
	s_add_u32 s44, s2, s44
	s_addc_u32 s45, s15, s45
	s_and_b64 s[54:55], s[38:39], exec
	s_cselect_b32 s21, s45, s27
	s_cselect_b32 s53, s44, s26
	s_add_u32 vcc_lo, s10, 0x40080
	s_addc_u32 vcc_hi, s11, 0
	s_add_u32 s54, s26, 0x100
	v_mov_b32_e32 v2, 0
	s_addc_u32 s55, s27, 0
	s_mov_b32 s56, -2
	v_mov_b32_e32 v3, v2
	v_mov_b32_e32 v4, v2
	v_mov_b32_e32 v5, v2
	v_mov_b32_e32 v6, v2
	v_mov_b32_e32 v7, v2
	v_mov_b32_e32 v8, v2
	v_mov_b32_e32 v9, v2
	v_mov_b32_e32 v10, v2
	v_mov_b32_e32 v11, v2
	v_mov_b32_e32 v12, v2
	v_mov_b32_e32 v13, v2
	v_mov_b32_e32 v18, v2
	v_mov_b32_e32 v19, v2
	v_mov_b32_e32 v20, v2
	v_mov_b32_e32 v21, v2
	v_mov_b32_e32 v26, v2
	v_mov_b32_e32 v27, v2
	v_mov_b32_e32 v28, v2
	v_mov_b32_e32 v29, v2
	v_mov_b32_e32 v34, v2
	v_mov_b32_e32 v35, v2
	v_mov_b32_e32 v36, v2
	v_mov_b32_e32 v37, v2
	v_mov_b32_e32 v42, v2
	v_mov_b32_e32 v43, v2
	v_mov_b32_e32 v44, v2
	v_mov_b32_e32 v45, v2
	v_mov_b32_e32 v50, v2
	v_mov_b32_e32 v51, v2
	v_mov_b32_e32 v52, v2
	v_mov_b32_e32 v53, v2
	v_mov_b32_e32 v14, v2
	v_mov_b32_e32 v15, v2
	v_mov_b32_e32 v16, v2
	v_mov_b32_e32 v17, v2
	v_mov_b32_e32 v22, v2
	v_mov_b32_e32 v23, v2
	v_mov_b32_e32 v24, v2
	v_mov_b32_e32 v25, v2
	v_mov_b32_e32 v30, v2
	v_mov_b32_e32 v31, v2
	v_mov_b32_e32 v32, v2
	v_mov_b32_e32 v33, v2
	v_mov_b32_e32 v38, v2
	v_mov_b32_e32 v39, v2
	v_mov_b32_e32 v40, v2
	v_mov_b32_e32 v41, v2
	v_mov_b32_e32 v46, v2
	v_mov_b32_e32 v47, v2
	v_mov_b32_e32 v48, v2
	v_mov_b32_e32 v49, v2
	v_mov_b32_e32 v54, v2
	v_mov_b32_e32 v55, v2
	v_mov_b32_e32 v56, v2
	v_mov_b32_e32 v57, v2
	v_mov_b32_e32 v58, v2
	v_mov_b32_e32 v59, v2
	v_mov_b32_e32 v60, v2
	v_mov_b32_e32 v61, v2
	v_mov_b32_e32 v62, v2
	v_mov_b32_e32 v63, v2
	v_mov_b32_e32 v64, v2
	v_mov_b32_e32 v65, v2
	v_mov_b32_e32 v66, v2
	v_mov_b32_e32 v67, v2
	v_mov_b32_e32 v68, v2
	v_mov_b32_e32 v69, v2
	v_mov_b32_e32 v70, v2
	v_mov_b32_e32 v71, v2
	v_mov_b32_e32 v72, v2
	v_mov_b32_e32 v73, v2
	v_mov_b32_e32 v74, v2
	v_mov_b32_e32 v75, v2
	v_mov_b32_e32 v76, v2
	v_mov_b32_e32 v77, v2
	v_mov_b32_e32 v82, v2
	v_mov_b32_e32 v83, v2
	v_mov_b32_e32 v84, v2
	v_mov_b32_e32 v85, v2
	v_mov_b32_e32 v90, v2
	v_mov_b32_e32 v91, v2
	v_mov_b32_e32 v92, v2
	v_mov_b32_e32 v93, v2
	v_mov_b32_e32 v98, v2
	v_mov_b32_e32 v99, v2
	v_mov_b32_e32 v100, v2
	v_mov_b32_e32 v101, v2
	v_mov_b32_e32 v106, v2
	v_mov_b32_e32 v107, v2
	v_mov_b32_e32 v108, v2
	v_mov_b32_e32 v109, v2
	v_mov_b32_e32 v114, v2
	v_mov_b32_e32 v115, v2
	v_mov_b32_e32 v116, v2
	v_mov_b32_e32 v117, v2
	v_mov_b32_e32 v78, v2
	v_mov_b32_e32 v79, v2
	v_mov_b32_e32 v80, v2
	v_mov_b32_e32 v81, v2
	v_mov_b32_e32 v86, v2
	v_mov_b32_e32 v87, v2
	v_mov_b32_e32 v88, v2
	v_mov_b32_e32 v89, v2
	v_mov_b32_e32 v94, v2
	v_mov_b32_e32 v95, v2
	v_mov_b32_e32 v96, v2
	v_mov_b32_e32 v97, v2
	v_mov_b32_e32 v102, v2
	v_mov_b32_e32 v103, v2
	v_mov_b32_e32 v104, v2
	v_mov_b32_e32 v105, v2
	v_mov_b32_e32 v110, v2
	v_mov_b32_e32 v111, v2
	v_mov_b32_e32 v112, v2
	v_mov_b32_e32 v113, v2
	v_mov_b32_e32 v118, v2
	v_mov_b32_e32 v119, v2
	v_mov_b32_e32 v120, v2
	v_mov_b32_e32 v121, v2
	v_mov_b32_e32 v122, v2
	v_mov_b32_e32 v123, v2
	v_mov_b32_e32 v124, v2
	v_mov_b32_e32 v125, v2
	v_mov_b32_e32 v126, v2
	v_mov_b32_e32 v127, v2
	v_mov_b32_e32 v128, v2
	v_mov_b32_e32 v129, v2
	s_cmp_eq_u32 s100, 0
	s_cbranch_scc1 .LBB0_73
	s_add_u32 s10, vcc_lo, 0xfffc0080
	s_addc_u32 s11, vcc_hi, -1
	s_add_i32 s57, 0, 0x10000
	s_cmp_eq_u32 s56, 12
	s_cselect_b32 s11, s35, s11
	s_cselect_b32 s10, s52, s10
	v_add_u32_e32 v140, s57, v143
	s_cselect_b32 s27, s21, s55
	s_cselect_b32 s26, s53, s54
	s_add_i32 s60, 0, 0x14000
	ds_read_b128 v[146:149], v140
	ds_read_b128 v[150:153], v140 offset:1024
	ds_read_b128 v[154:157], v140 offset:2048
	ds_read_b128 v[158:161], v140 offset:3072
	v_add_u32_e32 v140, s60, v143
	ds_read_b128 v[162:165], v140
	ds_read_b128 v[166:169], v140 offset:1024
	ds_read_b128 v[170:173], v140 offset:2048
	ds_read_b128 v[174:177], v140 offset:3072
	v_lshl_add_u64 v[140:141], vcc, 0, v[136:137]
	s_add_i32 m0, s23, 0xc000
	ds_read_b128 v[178:181], v145
	ds_read_b128 v[182:185], v145 offset:1024
	ds_read_b128 v[200:203], v145 offset:2048
	ds_read_b128 v[204:207], v145 offset:3072
	ds_read_b128 v[208:211], v145 offset:4096
	ds_read_b128 v[212:215], v145 offset:5120
	ds_read_b128 v[216:219], v145 offset:6144
	ds_read_b128 v[220:223], v145 offset:7168
	global_load_lds_dwordx4 v[140:141], off
	v_lshl_add_u64 v[140:141], vcc, 0, v[138:139]
	s_add_i32 m0, s23, 0xe000
	s_nop 0
	global_load_lds_dwordx4 v[140:141], off
	s_waitcnt vmcnt(24)
	s_waitcnt lgkmcnt(0)
	s_barrier
	s_setprio 1
	s_waitcnt lgkmcnt(0)
	v_mfma_f32_16x16x32_bf16 v[126:129], v[146:149], v[178:181], v[126:129]
	v_mfma_f32_16x16x32_bf16 v[122:125], v[154:157], v[178:181], v[122:125]
	v_mfma_f32_16x16x32_bf16 v[118:121], v[146:149], v[200:203], v[118:121]
	v_mfma_f32_16x16x32_bf16 v[110:113], v[154:157], v[200:203], v[110:113]
	v_mfma_f32_16x16x32_bf16 v[102:105], v[146:149], v[208:211], v[102:105]
	v_mfma_f32_16x16x32_bf16 v[94:97], v[154:157], v[208:211], v[94:97]
	v_mfma_f32_16x16x32_bf16 v[86:89], v[146:149], v[216:219], v[86:89]
	v_mfma_f32_16x16x32_bf16 v[78:81], v[154:157], v[216:219], v[78:81]
	v_mfma_f32_16x16x32_bf16 v[126:129], v[150:153], v[182:185], v[126:129]
	v_mfma_f32_16x16x32_bf16 v[122:125], v[158:161], v[182:185], v[122:125]
	v_mfma_f32_16x16x32_bf16 v[118:121], v[150:153], v[204:207], v[118:121]
	v_mfma_f32_16x16x32_bf16 v[110:113], v[158:161], v[204:207], v[110:113]
	v_mfma_f32_16x16x32_bf16 v[102:105], v[150:153], v[212:215], v[102:105]
	v_mfma_f32_16x16x32_bf16 v[94:97], v[158:161], v[212:215], v[94:97]
	v_mfma_f32_16x16x32_bf16 v[86:89], v[150:153], v[220:223], v[86:89]
	v_mfma_f32_16x16x32_bf16 v[78:81], v[158:161], v[220:223], v[78:81]
	s_setprio 0
	s_setprio 1
	v_mfma_f32_16x16x32_bf16 v[114:117], v[162:165], v[178:181], v[114:117]
	v_mfma_f32_16x16x32_bf16 v[106:109], v[170:173], v[178:181], v[106:109]
	v_mfma_f32_16x16x32_bf16 v[98:101], v[162:165], v[200:203], v[98:101]
	v_mfma_f32_16x16x32_bf16 v[90:93], v[170:173], v[200:203], v[90:93]
	v_mfma_f32_16x16x32_bf16 v[82:85], v[162:165], v[208:211], v[82:85]
	v_mfma_f32_16x16x32_bf16 v[74:77], v[170:173], v[208:211], v[74:77]
	v_mfma_f32_16x16x32_bf16 v[70:73], v[162:165], v[216:219], v[70:73]
	v_mfma_f32_16x16x32_bf16 v[66:69], v[170:173], v[216:219], v[66:69]
	v_mfma_f32_16x16x32_bf16 v[114:117], v[166:169], v[182:185], v[114:117]
	v_mfma_f32_16x16x32_bf16 v[106:109], v[174:177], v[182:185], v[106:109]
	v_mfma_f32_16x16x32_bf16 v[98:101], v[166:169], v[204:207], v[98:101]
	v_mfma_f32_16x16x32_bf16 v[90:93], v[174:177], v[204:207], v[90:93]
	v_mfma_f32_16x16x32_bf16 v[82:85], v[166:169], v[212:215], v[82:85]
	v_mfma_f32_16x16x32_bf16 v[74:77], v[174:177], v[212:215], v[74:77]
	v_mfma_f32_16x16x32_bf16 v[70:73], v[166:169], v[220:223], v[70:73]
	v_mfma_f32_16x16x32_bf16 v[66:69], v[174:177], v[220:223], v[66:69]
	s_setprio 0
	s_barrier
	s_add_i32 s57, s57, s22
	v_lshl_add_u64 v[140:141], s[26:27], 0, v[0:1]
	s_mov_b32 m0, s57
	ds_read_b128 v[178:181], v145 offset:16384
	ds_read_b128 v[182:185], v145 offset:17408
	ds_read_b128 v[200:203], v145 offset:18432
	ds_read_b128 v[204:207], v145 offset:19456
	ds_read_b128 v[208:211], v145 offset:20480
	ds_read_b128 v[212:215], v145 offset:21504
	ds_read_b128 v[216:219], v145 offset:22528
	ds_read_b128 v[220:223], v145 offset:23552
	global_load_lds_dwordx4 v[140:141], off
	s_add_i32 m0, s57, 0x2000
	s_add_u32 s58, s26, 0x40000
	v_lshl_add_u64 v[190:191], s[26:27], 0, v[130:131]
	s_addc_u32 s59, s27, 0
	s_add_i32 s57, s60, s22
	global_load_lds_dwordx4 v[190:191], off
	v_lshl_add_u64 v[192:193], s[58:59], 0, v[0:1]
	s_mov_b32 m0, s57
	v_lshl_add_u64 v[224:225], s[10:11], 0, v[132:133]
	global_load_lds_dwordx4 v[192:193], off
	v_lshl_add_u64 v[192:193], s[58:59], 0, v[130:131]
	s_add_i32 m0, s57, 0x2000
	s_nop 0
	global_load_lds_dwordx4 v[192:193], off
	v_lshl_add_u64 v[192:193], s[10:11], 0, v[134:135]
	s_mov_b32 m0, s23
	s_nop 0
	global_load_lds_dwordx4 v[192:193], off
	s_mov_b32 m0, s40
	s_nop 0
	global_load_lds_dwordx4 v[224:225], off
	s_waitcnt vmcnt(24)
	s_waitcnt lgkmcnt(0)
	s_barrier
	s_setprio 1
	s_waitcnt lgkmcnt(0)
	v_mfma_f32_16x16x32_bf16 v[62:65], v[146:149], v[178:181], v[62:65]
	v_mfma_f32_16x16x32_bf16 v[58:61], v[154:157], v[178:181], v[58:61]
	v_mfma_f32_16x16x32_bf16 v[54:57], v[146:149], v[200:203], v[54:57]
	v_mfma_f32_16x16x32_bf16 v[46:49], v[154:157], v[200:203], v[46:49]
	v_mfma_f32_16x16x32_bf16 v[38:41], v[146:149], v[208:211], v[38:41]
	v_mfma_f32_16x16x32_bf16 v[30:33], v[154:157], v[208:211], v[30:33]
	v_mfma_f32_16x16x32_bf16 v[22:25], v[146:149], v[216:219], v[22:25]
	v_mfma_f32_16x16x32_bf16 v[14:17], v[154:157], v[216:219], v[14:17]
	v_mfma_f32_16x16x32_bf16 v[62:65], v[150:153], v[182:185], v[62:65]
	v_mfma_f32_16x16x32_bf16 v[58:61], v[158:161], v[182:185], v[58:61]
	v_mfma_f32_16x16x32_bf16 v[54:57], v[150:153], v[204:207], v[54:57]
	v_mfma_f32_16x16x32_bf16 v[46:49], v[158:161], v[204:207], v[46:49]
	v_mfma_f32_16x16x32_bf16 v[38:41], v[150:153], v[212:215], v[38:41]
	v_mfma_f32_16x16x32_bf16 v[30:33], v[158:161], v[212:215], v[30:33]
	v_mfma_f32_16x16x32_bf16 v[22:25], v[150:153], v[220:223], v[22:25]
	v_mfma_f32_16x16x32_bf16 v[14:17], v[158:161], v[220:223], v[14:17]
	s_setprio 0
	s_setprio 1
	v_mfma_f32_16x16x32_bf16 v[50:53], v[162:165], v[178:181], v[50:53]
	v_mfma_f32_16x16x32_bf16 v[42:45], v[170:173], v[178:181], v[42:45]
	v_mfma_f32_16x16x32_bf16 v[34:37], v[162:165], v[200:203], v[34:37]
	v_mfma_f32_16x16x32_bf16 v[26:29], v[170:173], v[200:203], v[26:29]
	v_mfma_f32_16x16x32_bf16 v[18:21], v[162:165], v[208:211], v[18:21]
	v_mfma_f32_16x16x32_bf16 v[10:13], v[170:173], v[208:211], v[10:13]
	v_mfma_f32_16x16x32_bf16 v[6:9], v[162:165], v[216:219], v[6:9]
	v_mfma_f32_16x16x32_bf16 v[2:5], v[170:173], v[216:219], v[2:5]
	v_mfma_f32_16x16x32_bf16 v[50:53], v[166:169], v[182:185], v[50:53]
	v_mfma_f32_16x16x32_bf16 v[42:45], v[174:177], v[182:185], v[42:45]
	v_mfma_f32_16x16x32_bf16 v[34:37], v[166:169], v[204:207], v[34:37]
	v_mfma_f32_16x16x32_bf16 v[26:29], v[174:177], v[204:207], v[26:29]
	v_mfma_f32_16x16x32_bf16 v[18:21], v[166:169], v[212:215], v[18:21]
	v_mfma_f32_16x16x32_bf16 v[10:13], v[174:177], v[212:215], v[10:13]
	v_mfma_f32_16x16x32_bf16 v[6:9], v[166:169], v[220:223], v[6:9]
	v_mfma_f32_16x16x32_bf16 v[2:5], v[174:177], v[220:223], v[2:5]
	s_setprio 0
	s_barrier
	s_branch .Lg73_mid

.Lg73_mid:
	s_add_i32 s57, 0, 0x18000
	s_add_i32 s58, 0, 0x1c000
	v_add_u32_e32 v158, s57, v143
	v_add_u32_e32 v174, s58, v143
	ds_read_b128 v[146:149], v158
	ds_read_b128 v[150:153], v158 offset:1024
	ds_read_b128 v[154:157], v158 offset:2048
	ds_read_b128 v[158:161], v158 offset:3072
	ds_read_b128 v[162:165], v174
	ds_read_b128 v[166:169], v174 offset:1024
	ds_read_b128 v[170:173], v174 offset:2048
	ds_read_b128 v[174:177], v174 offset:3072
	s_add_u32 s10, s10, 0x40000
	s_addc_u32 s11, s11, 0
	s_mov_b32 m0, s41
	v_lshl_add_u64 v[226:227], s[10:11], 0, v[134:135]
	ds_read_b128 v[178:181], v145 offset:32768
	ds_read_b128 v[182:185], v145 offset:33792
	ds_read_b128 v[200:203], v145 offset:34816
	ds_read_b128 v[204:207], v145 offset:35840
	ds_read_b128 v[208:211], v145 offset:36864
	ds_read_b128 v[212:215], v145 offset:37888
	ds_read_b128 v[216:219], v145 offset:38912
	ds_read_b128 v[220:223], v145 offset:39936
	global_load_lds_dwordx4 v[226:227], off
	v_lshl_add_u64 v[226:227], s[10:11], 0, v[132:133]
	s_mov_b32 m0, s48
	s_nop 0
	global_load_lds_dwordx4 v[226:227], off
	s_waitcnt vmcnt(8)
	s_waitcnt lgkmcnt(0)
	s_barrier
	s_setprio 1
	s_waitcnt lgkmcnt(0)
	v_mfma_f32_16x16x32_bf16 v[126:129], v[146:149], v[178:181], v[126:129]
	v_mfma_f32_16x16x32_bf16 v[122:125], v[154:157], v[178:181], v[122:125]
	v_mfma_f32_16x16x32_bf16 v[118:121], v[146:149], v[200:203], v[118:121]
	v_mfma_f32_16x16x32_bf16 v[110:113], v[154:157], v[200:203], v[110:113]
	v_mfma_f32_16x16x32_bf16 v[102:105], v[146:149], v[208:211], v[102:105]
	v_mfma_f32_16x16x32_bf16 v[94:97], v[154:157], v[208:211], v[94:97]
	v_mfma_f32_16x16x32_bf16 v[86:89], v[146:149], v[216:219], v[86:89]
	v_mfma_f32_16x16x32_bf16 v[78:81], v[154:157], v[216:219], v[78:81]
	v_mfma_f32_16x16x32_bf16 v[126:129], v[150:153], v[182:185], v[126:129]
	v_mfma_f32_16x16x32_bf16 v[122:125], v[158:161], v[182:185], v[122:125]
	v_mfma_f32_16x16x32_bf16 v[118:121], v[150:153], v[204:207], v[118:121]
	v_mfma_f32_16x16x32_bf16 v[110:113], v[158:161], v[204:207], v[110:113]
	v_mfma_f32_16x16x32_bf16 v[102:105], v[150:153], v[212:215], v[102:105]
	v_mfma_f32_16x16x32_bf16 v[94:97], v[158:161], v[212:215], v[94:97]
	v_mfma_f32_16x16x32_bf16 v[86:89], v[150:153], v[220:223], v[86:89]
	v_mfma_f32_16x16x32_bf16 v[78:81], v[158:161], v[220:223], v[78:81]
	s_setprio 0
	s_setprio 1
	v_mfma_f32_16x16x32_bf16 v[114:117], v[162:165], v[178:181], v[114:117]
	v_mfma_f32_16x16x32_bf16 v[106:109], v[170:173], v[178:181], v[106:109]
	v_mfma_f32_16x16x32_bf16 v[98:101], v[162:165], v[200:203], v[98:101]
	v_mfma_f32_16x16x32_bf16 v[90:93], v[170:173], v[200:203], v[90:93]
	v_mfma_f32_16x16x32_bf16 v[82:85], v[162:165], v[208:211], v[82:85]
	v_mfma_f32_16x16x32_bf16 v[74:77], v[170:173], v[208:211], v[74:77]
	v_mfma_f32_16x16x32_bf16 v[70:73], v[162:165], v[216:219], v[70:73]
	v_mfma_f32_16x16x32_bf16 v[66:69], v[170:173], v[216:219], v[66:69]
	v_mfma_f32_16x16x32_bf16 v[114:117], v[166:169], v[182:185], v[114:117]
	v_mfma_f32_16x16x32_bf16 v[106:109], v[174:177], v[182:185], v[106:109]
	v_mfma_f32_16x16x32_bf16 v[98:101], v[166:169], v[204:207], v[98:101]
	v_mfma_f32_16x16x32_bf16 v[90:93], v[174:177], v[204:207], v[90:93]
	v_mfma_f32_16x16x32_bf16 v[82:85], v[166:169], v[212:215], v[82:85]
	v_mfma_f32_16x16x32_bf16 v[74:77], v[174:177], v[212:215], v[74:77]
	v_mfma_f32_16x16x32_bf16 v[70:73], v[166:169], v[220:223], v[70:73]
	v_mfma_f32_16x16x32_bf16 v[66:69], v[174:177], v[220:223], v[66:69]
	s_setprio 0
	s_barrier
	s_add_i32 s10, s57, s22
	v_lshl_add_u64 v[140:141], v[140:141], 0, s[46:47]
	s_mov_b32 m0, s10
	ds_read_b128 v[178:181], v145 offset:49152
	ds_read_b128 v[182:185], v145 offset:50176
	ds_read_b128 v[200:203], v145 offset:51200
	ds_read_b128 v[204:207], v145 offset:52224
	ds_read_b128 v[208:211], v145 offset:53248
	ds_read_b128 v[212:215], v145 offset:54272
	ds_read_b128 v[216:219], v145 offset:55296
	ds_read_b128 v[220:223], v145 offset:56320
	global_load_lds_dwordx4 v[140:141], off
	s_add_i32 m0, s10, 0x2000
	s_add_u32 s10, s26, 0x40080
	v_lshl_add_u64 v[140:141], v[190:191], 0, s[46:47]
	s_addc_u32 s11, s27, 0
	s_add_i32 s26, s58, s22
	global_load_lds_dwordx4 v[140:141], off
	v_lshl_add_u64 v[140:141], s[10:11], 0, v[0:1]
	s_mov_b32 m0, s26
	s_nop 0
	global_load_lds_dwordx4 v[140:141], off
	v_lshl_add_u64 v[140:141], s[10:11], 0, v[130:131]
	s_add_i32 m0, s26, 0x2000
	s_nop 0
	global_load_lds_dwordx4 v[140:141], off
	v_lshl_add_u64 v[140:141], v[192:193], 0, s[46:47]
	s_mov_b32 m0, s31
	s_nop 0
	global_load_lds_dwordx4 v[140:141], off
	v_lshl_add_u64 v[140:141], v[224:225], 0, s[46:47]
	s_mov_b32 m0, s95
	s_nop 0
	global_load_lds_dwordx4 v[140:141], off
	s_waitcnt vmcnt(8)
	s_waitcnt lgkmcnt(0)
	s_barrier
	s_setprio 1
	s_waitcnt lgkmcnt(0)
	v_mfma_f32_16x16x32_bf16 v[62:65], v[146:149], v[178:181], v[62:65]
	v_mfma_f32_16x16x32_bf16 v[58:61], v[154:157], v[178:181], v[58:61]
	v_mfma_f32_16x16x32_bf16 v[54:57], v[146:149], v[200:203], v[54:57]
	v_mfma_f32_16x16x32_bf16 v[46:49], v[154:157], v[200:203], v[46:49]
	v_mfma_f32_16x16x32_bf16 v[38:41], v[146:149], v[208:211], v[38:41]
	v_mfma_f32_16x16x32_bf16 v[30:33], v[154:157], v[208:211], v[30:33]
	v_mfma_f32_16x16x32_bf16 v[22:25], v[146:149], v[216:219], v[22:25]
	v_mfma_f32_16x16x32_bf16 v[14:17], v[154:157], v[216:219], v[14:17]
	v_mfma_f32_16x16x32_bf16 v[62:65], v[150:153], v[182:185], v[62:65]
	v_mfma_f32_16x16x32_bf16 v[58:61], v[158:161], v[182:185], v[58:61]
	v_mfma_f32_16x16x32_bf16 v[54:57], v[150:153], v[204:207], v[54:57]
	v_mfma_f32_16x16x32_bf16 v[46:49], v[158:161], v[204:207], v[46:49]
	v_mfma_f32_16x16x32_bf16 v[38:41], v[150:153], v[212:215], v[38:41]
	v_mfma_f32_16x16x32_bf16 v[30:33], v[158:161], v[212:215], v[30:33]
	v_mfma_f32_16x16x32_bf16 v[22:25], v[150:153], v[220:223], v[22:25]
	v_mfma_f32_16x16x32_bf16 v[14:17], v[158:161], v[220:223], v[14:17]
	s_setprio 0
	s_setprio 1
	v_mfma_f32_16x16x32_bf16 v[50:53], v[162:165], v[178:181], v[50:53]
	v_mfma_f32_16x16x32_bf16 v[42:45], v[170:173], v[178:181], v[42:45]
	v_mfma_f32_16x16x32_bf16 v[34:37], v[162:165], v[200:203], v[34:37]
	v_mfma_f32_16x16x32_bf16 v[26:29], v[170:173], v[200:203], v[26:29]
	v_mfma_f32_16x16x32_bf16 v[18:21], v[162:165], v[208:211], v[18:21]
	v_mfma_f32_16x16x32_bf16 v[10:13], v[170:173], v[208:211], v[10:13]
	v_mfma_f32_16x16x32_bf16 v[6:9], v[162:165], v[216:219], v[6:9]
	v_mfma_f32_16x16x32_bf16 v[2:5], v[170:173], v[216:219], v[2:5]
	v_mfma_f32_16x16x32_bf16 v[50:53], v[166:169], v[182:185], v[50:53]
	v_mfma_f32_16x16x32_bf16 v[42:45], v[174:177], v[182:185], v[42:45]
	v_mfma_f32_16x16x32_bf16 v[34:37], v[166:169], v[204:207], v[34:37]
	v_mfma_f32_16x16x32_bf16 v[26:29], v[174:177], v[204:207], v[26:29]
	v_mfma_f32_16x16x32_bf16 v[18:21], v[166:169], v[212:215], v[18:21]
	v_mfma_f32_16x16x32_bf16 v[10:13], v[174:177], v[212:215], v[10:13]
	v_mfma_f32_16x16x32_bf16 v[6:9], v[166:169], v[220:223], v[6:9]
	v_mfma_f32_16x16x32_bf16 v[2:5], v[174:177], v[220:223], v[2:5]
	s_setprio 0
	s_barrier
	s_add_i32 s56, s56, 2
	s_add_u32 vcc_lo, vcc_lo, 0x100
	s_addc_u32 vcc_hi, vcc_hi, 0
	s_add_u32 s54, s54, 0x100
	s_addc_u32 s55, s55, 0
	s_cmp_gt_u32 s56, 13
	s_cbranch_scc0 .LBB0_73
	s_and_b64 vcc, exec, s[18:19]
	s_cbranch_vccz .LBB0_76
	s_barrier
.LBB0_76:
	s_mov_b32 s100, 1
	s_ashr_i32 s10, s7, 31
	s_lshr_b32 s10, s10, 30
	s_lshl_b32 s21, s7, 8
	s_add_i32 s7, s7, s10
	s_ashr_i32 s10, s7, 2
	s_ashr_i32 s11, s10, 31
	s_lshl_b64 s[26:27], s[10:11], 26
	s_add_u32 s26, s12, s26
	s_addc_u32 s27, s13, s27
	s_lshl_b32 s7, s10, 10
	s_sub_i32 s7, s21, s7
	v_lshl_add_u32 v146, s6, 8, v142
	v_or_b32_e32 v140, s7, v144
	v_ashrrev_i32_e32 v141, 31, v140
	v_ashrrev_i32_e32 v147, 31, v146
	v_lshl_add_u64 v[148:149], v[140:141], 1, s[26:27]
	v_lshlrev_b64 v[140:141], 11, v[146:147]
	v_lshl_add_u64 v[140:141], v[148:149], 0, v[140:141]
	v_add_f32_e32 v147, 0, v124
	v_add_f32_e32 v124, 0, v122
	v_cvt_pk_bf16_f32 v122, v126, v127
	v_add_f32_e32 v150, 0, v123
	v_cvt_pk_bf16_f32 v123, v128, v129
	v_cvt_pk_bf16_f32 v124, v124, v150
	v_cvt_pk_bf16_f32 v125, v147, v125
	global_store_dwordx4 v[140:141], v[122:125], off
	s_nop 1
	v_add_f32_e32 v122, 0, v108
	v_add_f32_e32 v108, 0, v106
	v_cvt_pk_bf16_f32 v106, v114, v115
	v_add_f32_e32 v123, 0, v107
	v_cvt_pk_bf16_f32 v107, v116, v117
	v_cvt_pk_bf16_f32 v108, v108, v123
	v_cvt_pk_bf16_f32 v109, v122, v109
	global_store_dwordx4 v[140:141], v[106:109], off offset:256
	s_nop 1
	v_or_b32_e32 v106, 16, v146
	v_ashrrev_i32_e32 v107, 31, v106
	v_lshlrev_b64 v[106:107], 11, v[106:107]
	v_lshl_add_u64 v[114:115], v[148:149], 0, v[106:107]
	v_add_f32_e32 v106, 0, v118
	v_add_f32_e32 v107, 0, v120
	v_add_f32_e32 v108, 0, v121
	v_add_f32_e32 v109, 0, v119
	v_cvt_pk_bf16_f32 v106, v106, v109
	v_cvt_pk_bf16_f32 v107, v107, v108
	v_cvt_pk_bf16_f32 v108, v110, v111
	v_cvt_pk_bf16_f32 v109, v112, v113
	global_store_dwordx4 v[114:115], v[106:109], off
	s_nop 1
	v_add_f32_e32 v106, 0, v92
	v_add_f32_e32 v92, 0, v90
	v_cvt_pk_bf16_f32 v90, v98, v99
	v_add_f32_e32 v107, 0, v91
	v_cvt_pk_bf16_f32 v91, v100, v101
	v_cvt_pk_bf16_f32 v92, v92, v107
	v_cvt_pk_bf16_f32 v93, v106, v93
	global_store_dwordx4 v[114:115], v[90:93], off offset:256
	s_nop 1
	v_or_b32_e32 v90, 32, v146
	v_ashrrev_i32_e32 v91, 31, v90
	v_lshlrev_b64 v[90:91], 11, v[90:91]
	v_lshl_add_u64 v[98:99], v[148:149], 0, v[90:91]
	v_add_f32_e32 v90, 0, v102
	v_add_f32_e32 v91, 0, v104
	v_add_f32_e32 v92, 0, v105
	v_add_f32_e32 v93, 0, v103
	v_cvt_pk_bf16_f32 v90, v90, v93
	v_cvt_pk_bf16_f32 v91, v91, v92
	v_cvt_pk_bf16_f32 v92, v94, v95
	v_cvt_pk_bf16_f32 v93, v96, v97
	global_store_dwordx4 v[98:99], v[90:93], off
	s_nop 1
	v_add_f32_e32 v90, 0, v76
	v_add_f32_e32 v76, 0, v74
	v_cvt_pk_bf16_f32 v74, v82, v83
	v_add_f32_e32 v91, 0, v75
	v_cvt_pk_bf16_f32 v75, v84, v85
	v_cvt_pk_bf16_f32 v76, v76, v91
	v_cvt_pk_bf16_f32 v77, v90, v77
	global_store_dwordx4 v[98:99], v[74:77], off offset:256
	s_nop 1
	v_or_b32_e32 v74, 48, v146
	v_ashrrev_i32_e32 v75, 31, v74
	v_lshlrev_b64 v[74:75], 11, v[74:75]
	v_lshl_add_u64 v[82:83], v[148:149], 0, v[74:75]
	v_add_f32_e32 v74, 0, v86
	v_add_f32_e32 v75, 0, v88
	v_add_f32_e32 v76, 0, v89
	v_add_f32_e32 v77, 0, v87
	v_cvt_pk_bf16_f32 v74, v74, v77
	v_cvt_pk_bf16_f32 v75, v75, v76
	v_cvt_pk_bf16_f32 v76, v78, v79
	v_cvt_pk_bf16_f32 v77, v80, v81
	global_store_dwordx4 v[82:83], v[74:77], off
	s_nop 1
	v_add_f32_e32 v74, 0, v68
	v_add_f32_e32 v68, 0, v66
	v_add_f32_e32 v75, 0, v67
	v_cvt_pk_bf16_f32 v66, v70, v71
	v_cvt_pk_bf16_f32 v67, v72, v73
	v_cvt_pk_bf16_f32 v68, v68, v75
	s_mov_b32 s6, 0x40000
	v_cvt_pk_bf16_f32 v69, v74, v69
	global_store_dwordx4 v[82:83], v[66:69], off offset:256
	s_nop 1
	v_add_f32_e32 v68, 0, v60
	v_add_f32_e32 v60, 0, v58
	v_cvt_pk_bf16_f32 v58, v62, v63
	v_add_co_u32_e32 v62, vcc, s6, v140
	s_nop 0
	v_addc_co_u32_e32 v63, vcc, 0, v141, vcc
	v_add_f32_e32 v69, 0, v59
	v_cvt_pk_bf16_f32 v59, v64, v65
	v_cvt_pk_bf16_f32 v60, v60, v69
	v_cvt_pk_bf16_f32 v61, v68, v61
	global_store_dwordx4 v[62:63], v[58:61], off
	s_nop 1
	v_lshl_add_u64 v[66:67], v[140:141], 0, s[36:37]
	v_add_f32_e32 v58, 0, v44
	v_add_f32_e32 v44, 0, v42
	v_add_f32_e32 v59, 0, v43
	v_cvt_pk_bf16_f32 v42, v50, v51
	v_cvt_pk_bf16_f32 v43, v52, v53
	v_cvt_pk_bf16_f32 v44, v44, v59
	s_mov_b64 s[6:7], 0x48000
	v_cvt_pk_bf16_f32 v45, v58, v45
	global_store_dwordx4 v[66:67], v[42:45], off offset:256
	s_nop 1
	v_lshl_add_u64 v[50:51], v[140:141], 0, s[6:7]
	v_add_f32_e32 v43, 0, v56
	v_add_f32_e32 v44, 0, v57
	v_add_f32_e32 v42, 0, v54
	s_mov_b32 s6, 0x48000
	v_add_f32_e32 v45, 0, v55
	v_cvt_pk_bf16_f32 v42, v42, v45
	v_cvt_pk_bf16_f32 v43, v43, v44
	v_cvt_pk_bf16_f32 v44, v46, v47
	v_add_co_u32_e32 v46, vcc, s6, v140
	s_nop 0
	v_addc_co_u32_e32 v47, vcc, 0, v141, vcc
	v_cvt_pk_bf16_f32 v45, v48, v49
	global_store_dwordx4 v[46:47], v[42:45], off
	s_nop 1
	v_add_f32_e32 v42, 0, v28
	v_add_f32_e32 v28, 0, v26
	v_add_f32_e32 v43, 0, v27
	v_cvt_pk_bf16_f32 v26, v34, v35
	v_cvt_pk_bf16_f32 v27, v36, v37
	v_cvt_pk_bf16_f32 v28, v28, v43
	s_mov_b64 s[6:7], 0x50000
	v_cvt_pk_bf16_f32 v29, v42, v29
	global_store_dwordx4 v[50:51], v[26:29], off offset:256
	s_nop 1
	v_lshl_add_u64 v[34:35], v[140:141], 0, s[6:7]
	v_add_f32_e32 v27, 0, v40
	v_add_f32_e32 v28, 0, v41
	v_add_f32_e32 v26, 0, v38
	s_mov_b32 s6, 0x50000
	v_add_f32_e32 v29, 0, v39
	v_cvt_pk_bf16_f32 v26, v26, v29
	v_cvt_pk_bf16_f32 v27, v27, v28
	v_cvt_pk_bf16_f32 v28, v30, v31
	v_add_co_u32_e32 v30, vcc, s6, v140
	s_nop 0
	v_addc_co_u32_e32 v31, vcc, 0, v141, vcc
	v_cvt_pk_bf16_f32 v29, v32, v33
	global_store_dwordx4 v[30:31], v[26:29], off
	s_nop 1
	v_add_f32_e32 v26, 0, v12
	v_add_f32_e32 v12, 0, v10
	v_add_f32_e32 v27, 0, v11
	v_cvt_pk_bf16_f32 v10, v18, v19
	v_cvt_pk_bf16_f32 v11, v20, v21
	v_cvt_pk_bf16_f32 v12, v12, v27
	s_mov_b64 s[6:7], 0x58000
	v_cvt_pk_bf16_f32 v13, v26, v13
	global_store_dwordx4 v[34:35], v[10:13], off offset:256
	s_nop 1
	v_lshl_add_u64 v[18:19], v[140:141], 0, s[6:7]
	v_add_f32_e32 v11, 0, v24
	v_add_f32_e32 v12, 0, v25
	v_add_f32_e32 v10, 0, v22
	s_mov_b32 s6, 0x58000
	v_add_f32_e32 v13, 0, v23
	v_cvt_pk_bf16_f32 v10, v10, v13
	v_cvt_pk_bf16_f32 v11, v11, v12
	v_cvt_pk_bf16_f32 v12, v14, v15
	v_add_co_u32_e32 v14, vcc, s6, v140
	s_nop 0
	v_addc_co_u32_e32 v15, vcc, 0, v141, vcc
	v_cvt_pk_bf16_f32 v13, v16, v17
	global_store_dwordx4 v[14:15], v[10:13], off
	s_nop 1
	s_andn2_b64 vcc, exec, s[38:39]
	v_add_f32_e32 v10, 0, v4
	v_add_f32_e32 v4, 0, v2
	s_mov_b64 s[10:11], -1
	v_add_f32_e32 v11, 0, v3
	v_cvt_pk_bf16_f32 v2, v6, v7
	v_cvt_pk_bf16_f32 v3, v8, v9
	v_cvt_pk_bf16_f32 v4, v4, v11
	v_cvt_pk_bf16_f32 v5, v10, v5
	global_store_dwordx4 v[18:19], v[2:5], off offset:256
	s_nop 1
	s_cbranch_vccnz .LBB0_65
	s_andn2_b64 vcc, exec, s[0:1]
	s_cbranch_vccnz .LBB0_64
	s_barrier
	s_branch .LBB0_64
